# static s_setprio 1 for waves 4-7 during mixer-B (dilated window attention) blocks
# speedup vs baseline: 1.0014x; 1.0014x over previous
.LBB0_369:
	s_setprio 0
	v_readlane_b32 s16, v253, 21
	v_readlane_b32 s17, v253, 22
	v_readlane_b32 s18, v253, 23
	v_readlane_b32 s19, v253, 24
	v_readlane_b32 s20, v253, 25
	v_readlane_b32 s21, v253, 26
	v_readlane_b32 s22, v253, 27
	v_readlane_b32 s23, v253, 28
	s_mov_b64 s[4:5], s[16:17]
	s_lshl_b64 s[0:1], s[90:91], 2
	s_mov_b64 s[8:9], s[20:21]
	v_readlane_b32 s4, v253, 42
	s_add_u32 s0, s8, s0
	v_readlane_b32 s5, v253, 43
	s_addc_u32 s1, s9, s1
	s_mov_b64 s[2:3], -1
	s_and_b64 vcc, exec, s[4:5]
	s_barrier
	v_readlane_b32 s24, v253, 29
	v_readlane_b32 s25, v253, 30
	v_readlane_b32 s26, v253, 31
	v_readlane_b32 s27, v253, 32
	v_readlane_b32 s28, v253, 33
	v_readlane_b32 s29, v253, 34
	v_readlane_b32 s30, v253, 35
	v_readlane_b32 s31, v253, 36
	s_mov_b64 s[6:7], s[18:19]
	s_mov_b64 s[10:11], s[22:23]
	s_cbranch_vccz .LBB0_372
	v_readlane_b32 s2, v254, 1
	v_readlane_b32 s3, v254, 2
	s_andn2_b64 vcc, exec, s[2:3]
	v_readlane_b32 s6, v253, 50
	s_mov_b32 s7, s57
	s_cbranch_vccz .LBB0_413

.LBB0_375:
	v_readlane_b32 s98, v253, 39
	s_cmpk_ge_u32 s98, 0x100
	s_cbranch_scc0 .Lmixb_prio_skip
	s_setprio 1
